# P0 x-row loop: all four rows' loads in flight before the first reduce (4-deep instead of 2-deep)
# baseline (speedup 1.0000x reference)
.LBB0_248:
	s_or_b64 exec, exec, s[4:5]
	s_cmpk_gt_i32 s62, 0x1fff
	s_cbranch_scc1 .LBB0_253
	v_mbcnt_lo_u32_b32 v0, -1, 0
	v_mbcnt_hi_u32_b32 v0, -1, v0
	v_and_b32_e32 v1, 64, v0
	v_add_u32_e32 v1, 64, v1
	v_xor_b32_e32 v2, 1, v0
	v_cmp_lt_i32_e32 vcc, v2, v1
	s_ashr_i32 s63, s62, 31
	s_lshl_b64 s[4:5], s[62:63], 2
	v_cndmask_b32_e32 v2, v0, v2, vcc
	v_lshlrev_b32_e32 v38, 2, v2
	v_xor_b32_e32 v2, 2, v0
	v_cmp_lt_i32_e32 vcc, v2, v1
	s_add_u32 s3, s4, 0xfc04000
	s_waitcnt lgkmcnt(0)
	s_addc_u32 s20, s5, 0
	v_cndmask_b32_e32 v2, v0, v2, vcc
	v_lshlrev_b32_e32 v39, 2, v2
	v_xor_b32_e32 v2, 4, v0
	v_cmp_lt_i32_e32 vcc, v2, v1
	s_ashr_i32 s65, s64, 31
	s_lshl_b64 s[4:5], s[62:63], 12
	v_cndmask_b32_e32 v2, v0, v2, vcc
	v_lshlrev_b32_e32 v40, 2, v2
	v_xor_b32_e32 v2, 8, v0
	v_cmp_lt_i32_e32 vcc, v2, v1
	s_lshl_b64 s[10:11], s[64:65], 2
	v_lshl_or_b32 v32, v209, 3, s4
	v_cndmask_b32_e32 v2, v0, v2, vcc
	v_lshlrev_b32_e32 v41, 2, v2
	v_xor_b32_e32 v2, 16, v0
	v_cmp_lt_i32_e32 vcc, v2, v1
	v_mov_b32_e32 v33, s5
	s_lshl_b64 s[14:15], s[64:65], 12
	v_cndmask_b32_e32 v2, v0, v2, vcc
	v_lshlrev_b32_e32 v42, 2, v2
	v_xor_b32_e32 v2, 32, v0
	s_lshl_b64 s[4:5], s[62:63], 13
	v_cmp_lt_i32_e32 vcc, v2, v1
	s_add_u32 s4, s36, s4
	v_lshlrev_b32_e32 v34, 4, v209
	v_cndmask_b32_e32 v0, v0, v2, vcc
	v_mov_b32_e32 v35, 0
	s_addc_u32 s5, s37, s5
	v_lshlrev_b32_e32 v43, 2, v0
	v_lshl_add_u64 v[0:1], s[4:5], 0, v[34:35]
	s_mov_b64 s[4:5], 0x1000
	v_cmp_eq_u32_e64 s[0:1], 0, v209
	v_lshl_add_u64 v[36:37], v[0:1], 0, s[4:5]
	s_lshl_b64 s[16:17], s[64:65], 13
	v_mov_b32_e32 v34, 0x358637bd
	s_mov_b32 s21, 0xf800000
	v_mov_b32_e32 v44, 0x260
	s_movk_i32 s36, 0x7fff
	s_mov_b32 s37, 0xffff0000
	s_cmpk_lg_u32 s64, 0x800
	s_cbranch_scc1 .LBB0_251
	global_load_dwordx4 v[28:31], v[36:37], off offset:-4096 nt
	global_load_dwordx4 v[24:27], v[36:37], off offset:-3072 nt
	global_load_dwordx4 v[20:23], v[36:37], off offset:-2048 nt
	global_load_dwordx4 v[16:19], v[36:37], off offset:-1024 nt
	global_load_dwordx4 v[12:15], v[36:37], off nt
	global_load_dwordx4 v[8:11], v[36:37], off offset:1024 nt
	global_load_dwordx4 v[4:7], v[36:37], off offset:2048 nt
	global_load_dwordx4 v[0:3], v[36:37], off offset:3072 nt
	v_lshl_add_u64 v[36:37], v[36:37], 0, s[16:17]
	global_load_dwordx4 v[92:95], v[36:37], off offset:-4096 nt
	global_load_dwordx4 v[88:91], v[36:37], off offset:-3072 nt
	global_load_dwordx4 v[84:87], v[36:37], off offset:-2048 nt
	global_load_dwordx4 v[80:83], v[36:37], off offset:-1024 nt
	global_load_dwordx4 v[76:79], v[36:37], off nt
	global_load_dwordx4 v[72:75], v[36:37], off offset:1024 nt
	global_load_dwordx4 v[68:71], v[36:37], off offset:2048 nt
	global_load_dwordx4 v[64:67], v[36:37], off offset:3072 nt
	v_lshl_add_u64 v[36:37], v[36:37], 0, s[16:17]
	global_load_dwordx4 v[124:127], v[36:37], off offset:-4096 nt
	global_load_dwordx4 v[120:123], v[36:37], off offset:-3072 nt
	global_load_dwordx4 v[116:119], v[36:37], off offset:-2048 nt
	global_load_dwordx4 v[112:115], v[36:37], off offset:-1024 nt
	global_load_dwordx4 v[108:111], v[36:37], off nt
	global_load_dwordx4 v[104:107], v[36:37], off offset:1024 nt
	global_load_dwordx4 v[100:103], v[36:37], off offset:2048 nt
	global_load_dwordx4 v[96:99], v[36:37], off offset:3072 nt
	v_lshl_add_u64 v[36:37], v[36:37], 0, s[16:17]
	global_load_dwordx4 v[156:159], v[36:37], off offset:-4096 nt
	global_load_dwordx4 v[152:155], v[36:37], off offset:-3072 nt
	global_load_dwordx4 v[148:151], v[36:37], off offset:-2048 nt
	global_load_dwordx4 v[144:147], v[36:37], off offset:-1024 nt
	global_load_dwordx4 v[140:143], v[36:37], off nt
	global_load_dwordx4 v[136:139], v[36:37], off offset:1024 nt
	global_load_dwordx4 v[132:135], v[36:37], off offset:2048 nt
	global_load_dwordx4 v[128:131], v[36:37], off offset:3072 nt
	v_lshl_add_u64 v[36:37], v[36:37], 0, s[16:17]
	s_waitcnt vmcnt(24)
	v_mul_f32_e32 v45, v29, v29
	v_mul_f32_e32 v46, v31, v31
	v_mul_f32_e32 v47, v25, v25
	v_mul_f32_e32 v48, v27, v27
	v_mul_f32_e32 v49, v21, v21
	v_mul_f32_e32 v50, v23, v23
	v_fmac_f32_e32 v45, v28, v28
	v_fmac_f32_e32 v46, v30, v30
	v_fmac_f32_e32 v47, v24, v24
	v_fmac_f32_e32 v48, v26, v26
	v_mul_f32_e32 v51, v17, v17
	v_mul_f32_e32 v52, v19, v19
	v_fmac_f32_e32 v49, v20, v20
	v_fmac_f32_e32 v50, v22, v22
	v_add_f32_e32 v45, v45, v46
	v_add_f32_e32 v46, v47, v48
	v_mul_f32_e32 v53, v13, v13
	v_mul_f32_e32 v54, v15, v15
	v_fmac_f32_e32 v51, v16, v16
	v_fmac_f32_e32 v52, v18, v18
	v_add_f32_e32 v47, v49, v50
	v_add_f32_e32 v45, v45, v46
	v_mul_f32_e32 v55, v9, v9
	v_mul_f32_e32 v56, v11, v11
	v_fmac_f32_e32 v53, v12, v12
	v_fmac_f32_e32 v54, v14, v14
	v_add_f32_e32 v48, v51, v52
	v_add_f32_e32 v45, v45, v47
	v_mul_f32_e32 v57, v5, v5
	v_mul_f32_e32 v58, v7, v7
	v_fmac_f32_e32 v55, v8, v8
	v_fmac_f32_e32 v56, v10, v10
	v_add_f32_e32 v49, v53, v54
	v_add_f32_e32 v45, v45, v48
	v_mul_f32_e32 v59, v1, v1
	v_mul_f32_e32 v60, v3, v3
	v_fmac_f32_e32 v57, v4, v4
	v_fmac_f32_e32 v58, v6, v6
	v_add_f32_e32 v50, v55, v56
	v_add_f32_e32 v45, v45, v49
	v_fmac_f32_e32 v59, v0, v0
	v_fmac_f32_e32 v60, v2, v2
	v_add_f32_e32 v51, v57, v58
	v_add_f32_e32 v45, v45, v50
	v_add_f32_e32 v45, v45, v51
	v_add_f32_e32 v46, v59, v60
	v_add_f32_e32 v45, v45, v46
	ds_bpermute_b32 v46, v38, v45
	s_waitcnt lgkmcnt(0)
	v_add_f32_e32 v45, v45, v46
	ds_bpermute_b32 v46, v39, v45
	s_waitcnt lgkmcnt(0)
	v_add_f32_e32 v45, v45, v46
	ds_bpermute_b32 v46, v40, v45
	s_waitcnt lgkmcnt(0)
	v_add_f32_e32 v45, v45, v46
	ds_bpermute_b32 v46, v41, v45
	s_waitcnt lgkmcnt(0)
	v_add_f32_e32 v45, v45, v46
	ds_bpermute_b32 v46, v42, v45
	s_waitcnt lgkmcnt(0)
	v_add_f32_e32 v45, v45, v46
	ds_bpermute_b32 v46, v43, v45
	s_and_saveexec_b64 s[18:19], s[0:1]
	s_cbranch_execz .Lmy_xp_r0
	s_waitcnt lgkmcnt(0)
	v_add_f32_e32 v45, v45, v46
	v_fmamk_f32 v45, v45, 0x3a000000, v34
	v_mul_f32_e32 v46, 0x4f800000, v45
	v_cmp_gt_f32_e32 vcc, s21, v45
	s_nop 1
	v_cndmask_b32_e32 v45, v45, v46, vcc
	v_sqrt_f32_e32 v46, v45
	s_nop 0
	v_add_u32_e32 v47, -1, v46
	v_fma_f32 v49, -v47, v46, v45
	v_add_u32_e32 v48, 1, v46
	v_cmp_ge_f32_e64 s[4:5], 0, v49
	s_nop 1
	v_cndmask_b32_e64 v47, v46, v47, s[4:5]
	v_fma_f32 v46, -v48, v46, v45
	v_cmp_lt_f32_e64 s[4:5], 0, v46
	s_nop 1
	v_cndmask_b32_e64 v46, v47, v48, s[4:5]
	v_mul_f32_e32 v47, 0x37800000, v46
	v_cndmask_b32_e32 v46, v46, v47, vcc
	v_cmp_class_f32_e32 vcc, v45, v44
	s_nop 1
	v_cndmask_b32_e32 v45, v46, v45, vcc
	v_div_scale_f32 v46, s[4:5], v45, v45, 1.0
	v_rcp_f32_e32 v47, v46
	s_add_u32 s4, s26, s3
	s_addc_u32 s5, s27, s20
	v_fma_f32 v48, -v46, v47, 1.0
	v_fmac_f32_e32 v47, v48, v47
	v_div_scale_f32 v48, vcc, 1.0, v45, 1.0
	v_mul_f32_e32 v49, v48, v47
	v_fma_f32 v50, -v46, v49, v48
	v_fmac_f32_e32 v49, v50, v47
	v_fma_f32 v46, -v46, v49, v48
	v_div_fmas_f32 v46, v46, v47, v49
	v_div_fixup_f32 v45, v46, v45, 1.0
	global_store_dword v35, v45, s[4:5]
.Lmy_xp_r0:
	s_or_b64 exec, exec, s[18:19]
	v_bfe_u32 v45, v28, 16, 1
	v_add3_u32 v28, v28, v45, s36
	v_bfe_u32 v45, v29, 16, 1
	v_lshrrev_b32_e32 v28, 16, v28
	v_add3_u32 v29, v29, v45, s36
	v_and_or_b32 v28, v29, s37, v28
	v_bfe_u32 v29, v30, 16, 1
	v_add3_u32 v29, v30, v29, s36
	v_bfe_u32 v30, v31, 16, 1
	s_waitcnt lgkmcnt(0)
	v_lshl_add_u64 v[46:47], s[26:27], 0, v[32:33]
	v_lshrrev_b32_e32 v29, 16, v29
	v_add3_u32 v30, v31, v30, s36
	v_and_or_b32 v29, v30, s37, v29
	v_add_co_u32_e32 v30, vcc, 0x6400000, v46
	s_add_i32 s62, s62, s64
	s_nop 0
	v_addc_co_u32_e32 v31, vcc, 0, v47, vcc
	global_store_dwordx2 v[30:31], v[28:29], off
	v_bfe_u32 v28, v24, 16, 1
	v_add3_u32 v24, v24, v28, s36
	v_bfe_u32 v28, v25, 16, 1
	v_lshrrev_b32_e32 v24, 16, v24
	v_add3_u32 v25, v25, v28, s36
	v_and_or_b32 v24, v25, s37, v24
	v_bfe_u32 v25, v26, 16, 1
	v_add3_u32 v25, v26, v25, s36
	v_bfe_u32 v26, v27, 16, 1
	v_lshrrev_b32_e32 v25, 16, v25
	v_add3_u32 v26, v27, v26, s36
	v_and_or_b32 v25, v26, s37, v25
	global_store_dwordx2 v[30:31], v[24:25], off offset:512
	v_bfe_u32 v24, v20, 16, 1
	v_add3_u32 v20, v20, v24, s36
	v_bfe_u32 v24, v21, 16, 1
	v_lshrrev_b32_e32 v20, 16, v20
	v_add3_u32 v21, v21, v24, s36
	v_and_or_b32 v20, v21, s37, v20
	v_bfe_u32 v21, v22, 16, 1
	v_add3_u32 v21, v22, v21, s36
	v_bfe_u32 v22, v23, 16, 1
	v_lshrrev_b32_e32 v21, 16, v21
	v_add3_u32 v22, v23, v22, s36
	v_and_or_b32 v21, v22, s37, v21
	global_store_dwordx2 v[30:31], v[20:21], off offset:1024
	v_bfe_u32 v20, v16, 16, 1
	v_add3_u32 v16, v16, v20, s36
	v_bfe_u32 v20, v17, 16, 1
	v_lshrrev_b32_e32 v16, 16, v16
	v_add3_u32 v17, v17, v20, s36
	v_and_or_b32 v16, v17, s37, v16
	v_bfe_u32 v17, v18, 16, 1
	v_add3_u32 v17, v18, v17, s36
	v_bfe_u32 v18, v19, 16, 1
	v_lshrrev_b32_e32 v17, 16, v17
	v_add3_u32 v18, v19, v18, s36
	v_and_or_b32 v17, v18, s37, v17
	global_store_dwordx2 v[30:31], v[16:17], off offset:1536
	v_bfe_u32 v16, v12, 16, 1
	v_add3_u32 v12, v12, v16, s36
	v_bfe_u32 v16, v13, 16, 1
	v_lshrrev_b32_e32 v12, 16, v12
	v_add3_u32 v13, v13, v16, s36
	v_and_or_b32 v12, v13, s37, v12
	v_bfe_u32 v13, v14, 16, 1
	v_add3_u32 v13, v14, v13, s36
	v_bfe_u32 v14, v15, 16, 1
	v_lshrrev_b32_e32 v13, 16, v13
	v_add3_u32 v14, v15, v14, s36
	v_and_or_b32 v13, v14, s37, v13
	global_store_dwordx2 v[30:31], v[12:13], off offset:2048
	v_bfe_u32 v12, v8, 16, 1
	v_add3_u32 v8, v8, v12, s36
	v_bfe_u32 v12, v9, 16, 1
	v_lshrrev_b32_e32 v8, 16, v8
	v_add3_u32 v9, v9, v12, s36
	v_and_or_b32 v8, v9, s37, v8
	v_bfe_u32 v9, v10, 16, 1
	v_add3_u32 v9, v10, v9, s36
	v_bfe_u32 v10, v11, 16, 1
	v_lshrrev_b32_e32 v9, 16, v9
	v_add3_u32 v10, v11, v10, s36
	v_and_or_b32 v9, v10, s37, v9
	global_store_dwordx2 v[30:31], v[8:9], off offset:2560
	v_bfe_u32 v8, v4, 16, 1
	v_add3_u32 v4, v4, v8, s36
	v_bfe_u32 v8, v5, 16, 1
	v_lshrrev_b32_e32 v4, 16, v4
	v_add3_u32 v5, v5, v8, s36
	v_and_or_b32 v4, v5, s37, v4
	v_bfe_u32 v5, v6, 16, 1
	v_add3_u32 v5, v6, v5, s36
	v_bfe_u32 v6, v7, 16, 1
	v_lshrrev_b32_e32 v5, 16, v5
	v_add3_u32 v6, v7, v6, s36
	v_and_or_b32 v5, v6, s37, v5
	global_store_dwordx2 v[30:31], v[4:5], off offset:3072
	v_bfe_u32 v4, v0, 16, 1
	v_add3_u32 v0, v0, v4, s36
	v_bfe_u32 v4, v1, 16, 1
	v_lshrrev_b32_e32 v0, 16, v0
	v_add3_u32 v1, v1, v4, s36
	v_and_or_b32 v0, v1, s37, v0
	v_bfe_u32 v1, v2, 16, 1
	v_add3_u32 v1, v2, v1, s36
	v_bfe_u32 v2, v3, 16, 1
	s_add_u32 s3, s3, s10
	v_lshrrev_b32_e32 v1, 16, v1
	v_add3_u32 v2, v3, v2, s36
	s_addc_u32 s20, s20, s11
	v_and_or_b32 v1, v2, s37, v1
	v_lshl_add_u64 v[32:33], v[32:33], 0, s[14:15]
	global_store_dwordx2 v[30:31], v[0:1], off offset:3584
	s_waitcnt vmcnt(25)
	v_mul_f32_e32 v45, v93, v93
	v_mul_f32_e32 v46, v95, v95
	v_mul_f32_e32 v47, v89, v89
	v_mul_f32_e32 v48, v91, v91
	v_mul_f32_e32 v49, v85, v85
	v_mul_f32_e32 v50, v87, v87
	v_fmac_f32_e32 v45, v92, v92
	v_fmac_f32_e32 v46, v94, v94
	v_fmac_f32_e32 v47, v88, v88
	v_fmac_f32_e32 v48, v90, v90
	v_mul_f32_e32 v51, v81, v81
	v_mul_f32_e32 v52, v83, v83
	v_fmac_f32_e32 v49, v84, v84
	v_fmac_f32_e32 v50, v86, v86
	v_add_f32_e32 v45, v45, v46
	v_add_f32_e32 v46, v47, v48
	v_mul_f32_e32 v53, v77, v77
	v_mul_f32_e32 v54, v79, v79
	v_fmac_f32_e32 v51, v80, v80
	v_fmac_f32_e32 v52, v82, v82
	v_add_f32_e32 v47, v49, v50
	v_add_f32_e32 v45, v45, v46
	v_mul_f32_e32 v55, v73, v73
	v_mul_f32_e32 v56, v75, v75
	v_fmac_f32_e32 v53, v76, v76
	v_fmac_f32_e32 v54, v78, v78
	v_add_f32_e32 v48, v51, v52
	v_add_f32_e32 v45, v45, v47
	v_mul_f32_e32 v57, v69, v69
	v_mul_f32_e32 v58, v71, v71
	v_fmac_f32_e32 v55, v72, v72
	v_fmac_f32_e32 v56, v74, v74
	v_add_f32_e32 v49, v53, v54
	v_add_f32_e32 v45, v45, v48
	v_mul_f32_e32 v59, v65, v65
	v_mul_f32_e32 v60, v67, v67
	v_fmac_f32_e32 v57, v68, v68
	v_fmac_f32_e32 v58, v70, v70
	v_add_f32_e32 v50, v55, v56
	v_add_f32_e32 v45, v45, v49
	v_fmac_f32_e32 v59, v64, v64
	v_fmac_f32_e32 v60, v66, v66
	v_add_f32_e32 v51, v57, v58
	v_add_f32_e32 v45, v45, v50
	v_add_f32_e32 v45, v45, v51
	v_add_f32_e32 v46, v59, v60
	v_add_f32_e32 v45, v45, v46
	ds_bpermute_b32 v46, v38, v45
	s_waitcnt lgkmcnt(0)
	v_add_f32_e32 v45, v45, v46
	ds_bpermute_b32 v46, v39, v45
	s_waitcnt lgkmcnt(0)
	v_add_f32_e32 v45, v45, v46
	ds_bpermute_b32 v46, v40, v45
	s_waitcnt lgkmcnt(0)
	v_add_f32_e32 v45, v45, v46
	ds_bpermute_b32 v46, v41, v45
	s_waitcnt lgkmcnt(0)
	v_add_f32_e32 v45, v45, v46
	ds_bpermute_b32 v46, v42, v45
	s_waitcnt lgkmcnt(0)
	v_add_f32_e32 v45, v45, v46
	ds_bpermute_b32 v46, v43, v45
	s_and_saveexec_b64 s[18:19], s[0:1]
	s_cbranch_execz .Lmy_xp_r1
	s_waitcnt lgkmcnt(0)
	v_add_f32_e32 v45, v45, v46
	v_fmamk_f32 v45, v45, 0x3a000000, v34
	v_mul_f32_e32 v46, 0x4f800000, v45
	v_cmp_gt_f32_e32 vcc, s21, v45
	s_nop 1
	v_cndmask_b32_e32 v45, v45, v46, vcc
	v_sqrt_f32_e32 v46, v45
	s_nop 0
	v_add_u32_e32 v47, -1, v46
	v_fma_f32 v49, -v47, v46, v45
	v_add_u32_e32 v48, 1, v46
	v_cmp_ge_f32_e64 s[4:5], 0, v49
	s_nop 1
	v_cndmask_b32_e64 v47, v46, v47, s[4:5]
	v_fma_f32 v46, -v48, v46, v45
	v_cmp_lt_f32_e64 s[4:5], 0, v46
	s_nop 1
	v_cndmask_b32_e64 v46, v47, v48, s[4:5]
	v_mul_f32_e32 v47, 0x37800000, v46
	v_cndmask_b32_e32 v46, v46, v47, vcc
	v_cmp_class_f32_e32 vcc, v45, v44
	s_nop 1
	v_cndmask_b32_e32 v45, v46, v45, vcc
	v_div_scale_f32 v46, s[4:5], v45, v45, 1.0
	v_rcp_f32_e32 v47, v46
	s_add_u32 s4, s26, s3
	s_addc_u32 s5, s27, s20
	v_fma_f32 v48, -v46, v47, 1.0
	v_fmac_f32_e32 v47, v48, v47
	v_div_scale_f32 v48, vcc, 1.0, v45, 1.0
	v_mul_f32_e32 v49, v48, v47
	v_fma_f32 v50, -v46, v49, v48
	v_fmac_f32_e32 v49, v50, v47
	v_fma_f32 v46, -v46, v49, v48
	v_div_fmas_f32 v46, v46, v47, v49
	v_div_fixup_f32 v45, v46, v45, 1.0
	global_store_dword v35, v45, s[4:5]
.Lmy_xp_r1:
	s_or_b64 exec, exec, s[18:19]
	v_bfe_u32 v45, v92, 16, 1
	v_add3_u32 v92, v92, v45, s36
	v_bfe_u32 v45, v93, 16, 1
	v_lshrrev_b32_e32 v92, 16, v92
	v_add3_u32 v93, v93, v45, s36
	v_and_or_b32 v92, v93, s37, v92
	v_bfe_u32 v93, v94, 16, 1
	v_add3_u32 v93, v94, v93, s36
	v_bfe_u32 v94, v95, 16, 1
	s_waitcnt lgkmcnt(0)
	v_lshl_add_u64 v[46:47], s[26:27], 0, v[32:33]
	v_lshrrev_b32_e32 v93, 16, v93
	v_add3_u32 v94, v95, v94, s36
	v_and_or_b32 v93, v94, s37, v93
	v_add_co_u32_e32 v94, vcc, 0x6400000, v46
	s_add_i32 s62, s62, s64
	s_nop 0
	v_addc_co_u32_e32 v95, vcc, 0, v47, vcc
	global_store_dwordx2 v[94:95], v[92:93], off
	v_bfe_u32 v92, v88, 16, 1
	v_add3_u32 v88, v88, v92, s36
	v_bfe_u32 v92, v89, 16, 1
	v_lshrrev_b32_e32 v88, 16, v88
	v_add3_u32 v89, v89, v92, s36
	v_and_or_b32 v88, v89, s37, v88
	v_bfe_u32 v89, v90, 16, 1
	v_add3_u32 v89, v90, v89, s36
	v_bfe_u32 v90, v91, 16, 1
	v_lshrrev_b32_e32 v89, 16, v89
	v_add3_u32 v90, v91, v90, s36
	v_and_or_b32 v89, v90, s37, v89
	global_store_dwordx2 v[94:95], v[88:89], off offset:512
	v_bfe_u32 v88, v84, 16, 1
	v_add3_u32 v84, v84, v88, s36
	v_bfe_u32 v88, v85, 16, 1
	v_lshrrev_b32_e32 v84, 16, v84
	v_add3_u32 v85, v85, v88, s36
	v_and_or_b32 v84, v85, s37, v84
	v_bfe_u32 v85, v86, 16, 1
	v_add3_u32 v85, v86, v85, s36
	v_bfe_u32 v86, v87, 16, 1
	v_lshrrev_b32_e32 v85, 16, v85
	v_add3_u32 v86, v87, v86, s36
	v_and_or_b32 v85, v86, s37, v85
	global_store_dwordx2 v[94:95], v[84:85], off offset:1024
	v_bfe_u32 v84, v80, 16, 1
	v_add3_u32 v80, v80, v84, s36
	v_bfe_u32 v84, v81, 16, 1
	v_lshrrev_b32_e32 v80, 16, v80
	v_add3_u32 v81, v81, v84, s36
	v_and_or_b32 v80, v81, s37, v80
	v_bfe_u32 v81, v82, 16, 1
	v_add3_u32 v81, v82, v81, s36
	v_bfe_u32 v82, v83, 16, 1
	v_lshrrev_b32_e32 v81, 16, v81
	v_add3_u32 v82, v83, v82, s36
	v_and_or_b32 v81, v82, s37, v81
	global_store_dwordx2 v[94:95], v[80:81], off offset:1536
	v_bfe_u32 v80, v76, 16, 1
	v_add3_u32 v76, v76, v80, s36
	v_bfe_u32 v80, v77, 16, 1
	v_lshrrev_b32_e32 v76, 16, v76
	v_add3_u32 v77, v77, v80, s36
	v_and_or_b32 v76, v77, s37, v76
	v_bfe_u32 v77, v78, 16, 1
	v_add3_u32 v77, v78, v77, s36
	v_bfe_u32 v78, v79, 16, 1
	v_lshrrev_b32_e32 v77, 16, v77
	v_add3_u32 v78, v79, v78, s36
	v_and_or_b32 v77, v78, s37, v77
	global_store_dwordx2 v[94:95], v[76:77], off offset:2048
	v_bfe_u32 v76, v72, 16, 1
	v_add3_u32 v72, v72, v76, s36
	v_bfe_u32 v76, v73, 16, 1
	v_lshrrev_b32_e32 v72, 16, v72
	v_add3_u32 v73, v73, v76, s36
	v_and_or_b32 v72, v73, s37, v72
	v_bfe_u32 v73, v74, 16, 1
	v_add3_u32 v73, v74, v73, s36
	v_bfe_u32 v74, v75, 16, 1
	v_lshrrev_b32_e32 v73, 16, v73
	v_add3_u32 v74, v75, v74, s36
	v_and_or_b32 v73, v74, s37, v73
	global_store_dwordx2 v[94:95], v[72:73], off offset:2560
	v_bfe_u32 v72, v68, 16, 1
	v_add3_u32 v68, v68, v72, s36
	v_bfe_u32 v72, v69, 16, 1
	v_lshrrev_b32_e32 v68, 16, v68
	v_add3_u32 v69, v69, v72, s36
	v_and_or_b32 v68, v69, s37, v68
	v_bfe_u32 v69, v70, 16, 1
	v_add3_u32 v69, v70, v69, s36
	v_bfe_u32 v70, v71, 16, 1
	v_lshrrev_b32_e32 v69, 16, v69
	v_add3_u32 v70, v71, v70, s36
	v_and_or_b32 v69, v70, s37, v69
	global_store_dwordx2 v[94:95], v[68:69], off offset:3072
	v_bfe_u32 v68, v64, 16, 1
	v_add3_u32 v64, v64, v68, s36
	v_bfe_u32 v68, v65, 16, 1
	v_lshrrev_b32_e32 v64, 16, v64
	v_add3_u32 v65, v65, v68, s36
	v_and_or_b32 v64, v65, s37, v64
	v_bfe_u32 v65, v66, 16, 1
	v_add3_u32 v65, v66, v65, s36
	v_bfe_u32 v66, v67, 16, 1
	s_add_u32 s3, s3, s10
	v_lshrrev_b32_e32 v65, 16, v65
	v_add3_u32 v66, v67, v66, s36
	s_addc_u32 s20, s20, s11
	v_and_or_b32 v65, v66, s37, v65
	v_lshl_add_u64 v[32:33], v[32:33], 0, s[14:15]
	global_store_dwordx2 v[94:95], v[64:65], off offset:3584
	s_waitcnt vmcnt(26)
	v_mul_f32_e32 v45, v125, v125
	v_mul_f32_e32 v46, v127, v127
	v_mul_f32_e32 v47, v121, v121
	v_mul_f32_e32 v48, v123, v123
	v_mul_f32_e32 v49, v117, v117
	v_mul_f32_e32 v50, v119, v119
	v_fmac_f32_e32 v45, v124, v124
	v_fmac_f32_e32 v46, v126, v126
	v_fmac_f32_e32 v47, v120, v120
	v_fmac_f32_e32 v48, v122, v122
	v_mul_f32_e32 v51, v113, v113
	v_mul_f32_e32 v52, v115, v115
	v_fmac_f32_e32 v49, v116, v116
	v_fmac_f32_e32 v50, v118, v118
	v_add_f32_e32 v45, v45, v46
	v_add_f32_e32 v46, v47, v48
	v_mul_f32_e32 v53, v109, v109
	v_mul_f32_e32 v54, v111, v111
	v_fmac_f32_e32 v51, v112, v112
	v_fmac_f32_e32 v52, v114, v114
	v_add_f32_e32 v47, v49, v50
	v_add_f32_e32 v45, v45, v46
	v_mul_f32_e32 v55, v105, v105
	v_mul_f32_e32 v56, v107, v107
	v_fmac_f32_e32 v53, v108, v108
	v_fmac_f32_e32 v54, v110, v110
	v_add_f32_e32 v48, v51, v52
	v_add_f32_e32 v45, v45, v47
	v_mul_f32_e32 v57, v101, v101
	v_mul_f32_e32 v58, v103, v103
	v_fmac_f32_e32 v55, v104, v104
	v_fmac_f32_e32 v56, v106, v106
	v_add_f32_e32 v49, v53, v54
	v_add_f32_e32 v45, v45, v48
	v_mul_f32_e32 v59, v97, v97
	v_mul_f32_e32 v60, v99, v99
	v_fmac_f32_e32 v57, v100, v100
	v_fmac_f32_e32 v58, v102, v102
	v_add_f32_e32 v50, v55, v56
	v_add_f32_e32 v45, v45, v49
	v_fmac_f32_e32 v59, v96, v96
	v_fmac_f32_e32 v60, v98, v98
	v_add_f32_e32 v51, v57, v58
	v_add_f32_e32 v45, v45, v50
	v_add_f32_e32 v45, v45, v51
	v_add_f32_e32 v46, v59, v60
	v_add_f32_e32 v45, v45, v46
	ds_bpermute_b32 v46, v38, v45
	s_waitcnt lgkmcnt(0)
	v_add_f32_e32 v45, v45, v46
	ds_bpermute_b32 v46, v39, v45
	s_waitcnt lgkmcnt(0)
	v_add_f32_e32 v45, v45, v46
	ds_bpermute_b32 v46, v40, v45
	s_waitcnt lgkmcnt(0)
	v_add_f32_e32 v45, v45, v46
	ds_bpermute_b32 v46, v41, v45
	s_waitcnt lgkmcnt(0)
	v_add_f32_e32 v45, v45, v46
	ds_bpermute_b32 v46, v42, v45
	s_waitcnt lgkmcnt(0)
	v_add_f32_e32 v45, v45, v46
	ds_bpermute_b32 v46, v43, v45
	s_and_saveexec_b64 s[18:19], s[0:1]
	s_cbranch_execz .Lmy_xp_r2
	s_waitcnt lgkmcnt(0)
	v_add_f32_e32 v45, v45, v46
	v_fmamk_f32 v45, v45, 0x3a000000, v34
	v_mul_f32_e32 v46, 0x4f800000, v45
	v_cmp_gt_f32_e32 vcc, s21, v45
	s_nop 1
	v_cndmask_b32_e32 v45, v45, v46, vcc
	v_sqrt_f32_e32 v46, v45
	s_nop 0
	v_add_u32_e32 v47, -1, v46
	v_fma_f32 v49, -v47, v46, v45
	v_add_u32_e32 v48, 1, v46
	v_cmp_ge_f32_e64 s[4:5], 0, v49
	s_nop 1
	v_cndmask_b32_e64 v47, v46, v47, s[4:5]
	v_fma_f32 v46, -v48, v46, v45
	v_cmp_lt_f32_e64 s[4:5], 0, v46
	s_nop 1
	v_cndmask_b32_e64 v46, v47, v48, s[4:5]
	v_mul_f32_e32 v47, 0x37800000, v46
	v_cndmask_b32_e32 v46, v46, v47, vcc
	v_cmp_class_f32_e32 vcc, v45, v44
	s_nop 1
	v_cndmask_b32_e32 v45, v46, v45, vcc
	v_div_scale_f32 v46, s[4:5], v45, v45, 1.0
	v_rcp_f32_e32 v47, v46
	s_add_u32 s4, s26, s3
	s_addc_u32 s5, s27, s20
	v_fma_f32 v48, -v46, v47, 1.0
	v_fmac_f32_e32 v47, v48, v47
	v_div_scale_f32 v48, vcc, 1.0, v45, 1.0
	v_mul_f32_e32 v49, v48, v47
	v_fma_f32 v50, -v46, v49, v48
	v_fmac_f32_e32 v49, v50, v47
	v_fma_f32 v46, -v46, v49, v48
	v_div_fmas_f32 v46, v46, v47, v49
	v_div_fixup_f32 v45, v46, v45, 1.0
	global_store_dword v35, v45, s[4:5]
.Lmy_xp_r2:
	s_or_b64 exec, exec, s[18:19]
	v_bfe_u32 v45, v124, 16, 1
	v_add3_u32 v124, v124, v45, s36
	v_bfe_u32 v45, v125, 16, 1
	v_lshrrev_b32_e32 v124, 16, v124
	v_add3_u32 v125, v125, v45, s36
	v_and_or_b32 v124, v125, s37, v124
	v_bfe_u32 v125, v126, 16, 1
	v_add3_u32 v125, v126, v125, s36
	v_bfe_u32 v126, v127, 16, 1
	s_waitcnt lgkmcnt(0)
	v_lshl_add_u64 v[46:47], s[26:27], 0, v[32:33]
	v_lshrrev_b32_e32 v125, 16, v125
	v_add3_u32 v126, v127, v126, s36
	v_and_or_b32 v125, v126, s37, v125
	v_add_co_u32_e32 v126, vcc, 0x6400000, v46
	s_add_i32 s62, s62, s64
	s_nop 0
	v_addc_co_u32_e32 v127, vcc, 0, v47, vcc
	global_store_dwordx2 v[126:127], v[124:125], off
	v_bfe_u32 v124, v120, 16, 1
	v_add3_u32 v120, v120, v124, s36
	v_bfe_u32 v124, v121, 16, 1
	v_lshrrev_b32_e32 v120, 16, v120
	v_add3_u32 v121, v121, v124, s36
	v_and_or_b32 v120, v121, s37, v120
	v_bfe_u32 v121, v122, 16, 1
	v_add3_u32 v121, v122, v121, s36
	v_bfe_u32 v122, v123, 16, 1
	v_lshrrev_b32_e32 v121, 16, v121
	v_add3_u32 v122, v123, v122, s36
	v_and_or_b32 v121, v122, s37, v121
	global_store_dwordx2 v[126:127], v[120:121], off offset:512
	v_bfe_u32 v120, v116, 16, 1
	v_add3_u32 v116, v116, v120, s36
	v_bfe_u32 v120, v117, 16, 1
	v_lshrrev_b32_e32 v116, 16, v116
	v_add3_u32 v117, v117, v120, s36
	v_and_or_b32 v116, v117, s37, v116
	v_bfe_u32 v117, v118, 16, 1
	v_add3_u32 v117, v118, v117, s36
	v_bfe_u32 v118, v119, 16, 1
	v_lshrrev_b32_e32 v117, 16, v117
	v_add3_u32 v118, v119, v118, s36
	v_and_or_b32 v117, v118, s37, v117
	global_store_dwordx2 v[126:127], v[116:117], off offset:1024
	v_bfe_u32 v116, v112, 16, 1
	v_add3_u32 v112, v112, v116, s36
	v_bfe_u32 v116, v113, 16, 1
	v_lshrrev_b32_e32 v112, 16, v112
	v_add3_u32 v113, v113, v116, s36
	v_and_or_b32 v112, v113, s37, v112
	v_bfe_u32 v113, v114, 16, 1
	v_add3_u32 v113, v114, v113, s36
	v_bfe_u32 v114, v115, 16, 1
	v_lshrrev_b32_e32 v113, 16, v113
	v_add3_u32 v114, v115, v114, s36
	v_and_or_b32 v113, v114, s37, v113
	global_store_dwordx2 v[126:127], v[112:113], off offset:1536
	v_bfe_u32 v112, v108, 16, 1
	v_add3_u32 v108, v108, v112, s36
	v_bfe_u32 v112, v109, 16, 1
	v_lshrrev_b32_e32 v108, 16, v108
	v_add3_u32 v109, v109, v112, s36
	v_and_or_b32 v108, v109, s37, v108
	v_bfe_u32 v109, v110, 16, 1
	v_add3_u32 v109, v110, v109, s36
	v_bfe_u32 v110, v111, 16, 1
	v_lshrrev_b32_e32 v109, 16, v109
	v_add3_u32 v110, v111, v110, s36
	v_and_or_b32 v109, v110, s37, v109
	global_store_dwordx2 v[126:127], v[108:109], off offset:2048
	v_bfe_u32 v108, v104, 16, 1
	v_add3_u32 v104, v104, v108, s36
	v_bfe_u32 v108, v105, 16, 1
	v_lshrrev_b32_e32 v104, 16, v104
	v_add3_u32 v105, v105, v108, s36
	v_and_or_b32 v104, v105, s37, v104
	v_bfe_u32 v105, v106, 16, 1
	v_add3_u32 v105, v106, v105, s36
	v_bfe_u32 v106, v107, 16, 1
	v_lshrrev_b32_e32 v105, 16, v105
	v_add3_u32 v106, v107, v106, s36
	v_and_or_b32 v105, v106, s37, v105
	global_store_dwordx2 v[126:127], v[104:105], off offset:2560
	v_bfe_u32 v104, v100, 16, 1
	v_add3_u32 v100, v100, v104, s36
	v_bfe_u32 v104, v101, 16, 1
	v_lshrrev_b32_e32 v100, 16, v100
	v_add3_u32 v101, v101, v104, s36
	v_and_or_b32 v100, v101, s37, v100
	v_bfe_u32 v101, v102, 16, 1
	v_add3_u32 v101, v102, v101, s36
	v_bfe_u32 v102, v103, 16, 1
	v_lshrrev_b32_e32 v101, 16, v101
	v_add3_u32 v102, v103, v102, s36
	v_and_or_b32 v101, v102, s37, v101
	global_store_dwordx2 v[126:127], v[100:101], off offset:3072
	v_bfe_u32 v100, v96, 16, 1
	v_add3_u32 v96, v96, v100, s36
	v_bfe_u32 v100, v97, 16, 1
	v_lshrrev_b32_e32 v96, 16, v96
	v_add3_u32 v97, v97, v100, s36
	v_and_or_b32 v96, v97, s37, v96
	v_bfe_u32 v97, v98, 16, 1
	v_add3_u32 v97, v98, v97, s36
	v_bfe_u32 v98, v99, 16, 1
	s_add_u32 s3, s3, s10
	v_lshrrev_b32_e32 v97, 16, v97
	v_add3_u32 v98, v99, v98, s36
	s_addc_u32 s20, s20, s11
	v_and_or_b32 v97, v98, s37, v97
	v_lshl_add_u64 v[32:33], v[32:33], 0, s[14:15]
	global_store_dwordx2 v[126:127], v[96:97], off offset:3584
	s_waitcnt vmcnt(27)
	v_mul_f32_e32 v45, v157, v157
	v_mul_f32_e32 v46, v159, v159
	v_mul_f32_e32 v47, v153, v153
	v_mul_f32_e32 v48, v155, v155
	v_mul_f32_e32 v49, v149, v149
	v_mul_f32_e32 v50, v151, v151
	v_fmac_f32_e32 v45, v156, v156
	v_fmac_f32_e32 v46, v158, v158
	v_fmac_f32_e32 v47, v152, v152
	v_fmac_f32_e32 v48, v154, v154
	v_mul_f32_e32 v51, v145, v145
	v_mul_f32_e32 v52, v147, v147
	v_fmac_f32_e32 v49, v148, v148
	v_fmac_f32_e32 v50, v150, v150
	v_add_f32_e32 v45, v45, v46
	v_add_f32_e32 v46, v47, v48
	v_mul_f32_e32 v53, v141, v141
	v_mul_f32_e32 v54, v143, v143
	v_fmac_f32_e32 v51, v144, v144
	v_fmac_f32_e32 v52, v146, v146
	v_add_f32_e32 v47, v49, v50
	v_add_f32_e32 v45, v45, v46
	v_mul_f32_e32 v55, v137, v137
	v_mul_f32_e32 v56, v139, v139
	v_fmac_f32_e32 v53, v140, v140
	v_fmac_f32_e32 v54, v142, v142
	v_add_f32_e32 v48, v51, v52
	v_add_f32_e32 v45, v45, v47
	v_mul_f32_e32 v57, v133, v133
	v_mul_f32_e32 v58, v135, v135
	v_fmac_f32_e32 v55, v136, v136
	v_fmac_f32_e32 v56, v138, v138
	v_add_f32_e32 v49, v53, v54
	v_add_f32_e32 v45, v45, v48
	v_mul_f32_e32 v59, v129, v129
	v_mul_f32_e32 v60, v131, v131
	v_fmac_f32_e32 v57, v132, v132
	v_fmac_f32_e32 v58, v134, v134
	v_add_f32_e32 v50, v55, v56
	v_add_f32_e32 v45, v45, v49
	v_fmac_f32_e32 v59, v128, v128
	v_fmac_f32_e32 v60, v130, v130
	v_add_f32_e32 v51, v57, v58
	v_add_f32_e32 v45, v45, v50
	v_add_f32_e32 v45, v45, v51
	v_add_f32_e32 v46, v59, v60
	v_add_f32_e32 v45, v45, v46
	ds_bpermute_b32 v46, v38, v45
	s_waitcnt lgkmcnt(0)
	v_add_f32_e32 v45, v45, v46
	ds_bpermute_b32 v46, v39, v45
	s_waitcnt lgkmcnt(0)
	v_add_f32_e32 v45, v45, v46
	ds_bpermute_b32 v46, v40, v45
	s_waitcnt lgkmcnt(0)
	v_add_f32_e32 v45, v45, v46
	ds_bpermute_b32 v46, v41, v45
	s_waitcnt lgkmcnt(0)
	v_add_f32_e32 v45, v45, v46
	ds_bpermute_b32 v46, v42, v45
	s_waitcnt lgkmcnt(0)
	v_add_f32_e32 v45, v45, v46
	ds_bpermute_b32 v46, v43, v45
	s_and_saveexec_b64 s[18:19], s[0:1]
	s_cbranch_execz .Lmy_xp_r3
	s_waitcnt lgkmcnt(0)
	v_add_f32_e32 v45, v45, v46
	v_fmamk_f32 v45, v45, 0x3a000000, v34
	v_mul_f32_e32 v46, 0x4f800000, v45
	v_cmp_gt_f32_e32 vcc, s21, v45
	s_nop 1
	v_cndmask_b32_e32 v45, v45, v46, vcc
	v_sqrt_f32_e32 v46, v45
	s_nop 0
	v_add_u32_e32 v47, -1, v46
	v_fma_f32 v49, -v47, v46, v45
	v_add_u32_e32 v48, 1, v46
	v_cmp_ge_f32_e64 s[4:5], 0, v49
	s_nop 1
	v_cndmask_b32_e64 v47, v46, v47, s[4:5]
	v_fma_f32 v46, -v48, v46, v45
	v_cmp_lt_f32_e64 s[4:5], 0, v46
	s_nop 1
	v_cndmask_b32_e64 v46, v47, v48, s[4:5]
	v_mul_f32_e32 v47, 0x37800000, v46
	v_cndmask_b32_e32 v46, v46, v47, vcc
	v_cmp_class_f32_e32 vcc, v45, v44
	s_nop 1
	v_cndmask_b32_e32 v45, v46, v45, vcc
	v_div_scale_f32 v46, s[4:5], v45, v45, 1.0
	v_rcp_f32_e32 v47, v46
	s_add_u32 s4, s26, s3
	s_addc_u32 s5, s27, s20
	v_fma_f32 v48, -v46, v47, 1.0
	v_fmac_f32_e32 v47, v48, v47
	v_div_scale_f32 v48, vcc, 1.0, v45, 1.0
	v_mul_f32_e32 v49, v48, v47
	v_fma_f32 v50, -v46, v49, v48
	v_fmac_f32_e32 v49, v50, v47
	v_fma_f32 v46, -v46, v49, v48
	v_div_fmas_f32 v46, v46, v47, v49
	v_div_fixup_f32 v45, v46, v45, 1.0
	global_store_dword v35, v45, s[4:5]
.Lmy_xp_r3:
	s_or_b64 exec, exec, s[18:19]
	v_bfe_u32 v45, v156, 16, 1
	v_add3_u32 v156, v156, v45, s36
	v_bfe_u32 v45, v157, 16, 1
	v_lshrrev_b32_e32 v156, 16, v156
	v_add3_u32 v157, v157, v45, s36
	v_and_or_b32 v156, v157, s37, v156
	v_bfe_u32 v157, v158, 16, 1
	v_add3_u32 v157, v158, v157, s36
	v_bfe_u32 v158, v159, 16, 1
	s_waitcnt lgkmcnt(0)
	v_lshl_add_u64 v[46:47], s[26:27], 0, v[32:33]
	v_lshrrev_b32_e32 v157, 16, v157
	v_add3_u32 v158, v159, v158, s36
	v_and_or_b32 v157, v158, s37, v157
	v_add_co_u32_e32 v158, vcc, 0x6400000, v46
	s_add_i32 s62, s62, s64
	s_nop 0
	v_addc_co_u32_e32 v159, vcc, 0, v47, vcc
	global_store_dwordx2 v[158:159], v[156:157], off
	v_bfe_u32 v156, v152, 16, 1
	v_add3_u32 v152, v152, v156, s36
	v_bfe_u32 v156, v153, 16, 1
	v_lshrrev_b32_e32 v152, 16, v152
	v_add3_u32 v153, v153, v156, s36
	v_and_or_b32 v152, v153, s37, v152
	v_bfe_u32 v153, v154, 16, 1
	v_add3_u32 v153, v154, v153, s36
	v_bfe_u32 v154, v155, 16, 1
	v_lshrrev_b32_e32 v153, 16, v153
	v_add3_u32 v154, v155, v154, s36
	v_and_or_b32 v153, v154, s37, v153
	global_store_dwordx2 v[158:159], v[152:153], off offset:512
	v_bfe_u32 v152, v148, 16, 1
	v_add3_u32 v148, v148, v152, s36
	v_bfe_u32 v152, v149, 16, 1
	v_lshrrev_b32_e32 v148, 16, v148
	v_add3_u32 v149, v149, v152, s36
	v_and_or_b32 v148, v149, s37, v148
	v_bfe_u32 v149, v150, 16, 1
	v_add3_u32 v149, v150, v149, s36
	v_bfe_u32 v150, v151, 16, 1
	v_lshrrev_b32_e32 v149, 16, v149
	v_add3_u32 v150, v151, v150, s36
	v_and_or_b32 v149, v150, s37, v149
	global_store_dwordx2 v[158:159], v[148:149], off offset:1024
	v_bfe_u32 v148, v144, 16, 1
	v_add3_u32 v144, v144, v148, s36
	v_bfe_u32 v148, v145, 16, 1
	v_lshrrev_b32_e32 v144, 16, v144
	v_add3_u32 v145, v145, v148, s36
	v_and_or_b32 v144, v145, s37, v144
	v_bfe_u32 v145, v146, 16, 1
	v_add3_u32 v145, v146, v145, s36
	v_bfe_u32 v146, v147, 16, 1
	v_lshrrev_b32_e32 v145, 16, v145
	v_add3_u32 v146, v147, v146, s36
	v_and_or_b32 v145, v146, s37, v145
	global_store_dwordx2 v[158:159], v[144:145], off offset:1536
	v_bfe_u32 v144, v140, 16, 1
	v_add3_u32 v140, v140, v144, s36
	v_bfe_u32 v144, v141, 16, 1
	v_lshrrev_b32_e32 v140, 16, v140
	v_add3_u32 v141, v141, v144, s36
	v_and_or_b32 v140, v141, s37, v140
	v_bfe_u32 v141, v142, 16, 1
	v_add3_u32 v141, v142, v141, s36
	v_bfe_u32 v142, v143, 16, 1
	v_lshrrev_b32_e32 v141, 16, v141
	v_add3_u32 v142, v143, v142, s36
	v_and_or_b32 v141, v142, s37, v141
	global_store_dwordx2 v[158:159], v[140:141], off offset:2048
	v_bfe_u32 v140, v136, 16, 1
	v_add3_u32 v136, v136, v140, s36
	v_bfe_u32 v140, v137, 16, 1
	v_lshrrev_b32_e32 v136, 16, v136
	v_add3_u32 v137, v137, v140, s36
	v_and_or_b32 v136, v137, s37, v136
	v_bfe_u32 v137, v138, 16, 1
	v_add3_u32 v137, v138, v137, s36
	v_bfe_u32 v138, v139, 16, 1
	v_lshrrev_b32_e32 v137, 16, v137
	v_add3_u32 v138, v139, v138, s36
	v_and_or_b32 v137, v138, s37, v137
	global_store_dwordx2 v[158:159], v[136:137], off offset:2560
	v_bfe_u32 v136, v132, 16, 1
	v_add3_u32 v132, v132, v136, s36
	v_bfe_u32 v136, v133, 16, 1
	v_lshrrev_b32_e32 v132, 16, v132
	v_add3_u32 v133, v133, v136, s36
	v_and_or_b32 v132, v133, s37, v132
	v_bfe_u32 v133, v134, 16, 1
	v_add3_u32 v133, v134, v133, s36
	v_bfe_u32 v134, v135, 16, 1
	v_lshrrev_b32_e32 v133, 16, v133
	v_add3_u32 v134, v135, v134, s36
	v_and_or_b32 v133, v134, s37, v133
	global_store_dwordx2 v[158:159], v[132:133], off offset:3072
	v_bfe_u32 v132, v128, 16, 1
	v_add3_u32 v128, v128, v132, s36
	v_bfe_u32 v132, v129, 16, 1
	v_lshrrev_b32_e32 v128, 16, v128
	v_add3_u32 v129, v129, v132, s36
	v_and_or_b32 v128, v129, s37, v128
	v_bfe_u32 v129, v130, 16, 1
	v_add3_u32 v129, v130, v129, s36
	v_bfe_u32 v130, v131, 16, 1
	s_add_u32 s3, s3, s10
	v_lshrrev_b32_e32 v129, 16, v129
	v_add3_u32 v130, v131, v130, s36
	s_addc_u32 s20, s20, s11
	v_and_or_b32 v129, v130, s37, v129
	v_lshl_add_u64 v[32:33], v[32:33], 0, s[14:15]
	global_store_dwordx2 v[158:159], v[128:129], off offset:3584
	s_branch .LBB0_253
	s_branch .LBB0_251
